# ffn_in: grid barrier after the 5 full tile rounds; the 128 workgroups without a sixth tile run the first 30 percent of convact while the others finish their sixth tile; convact proper covers the rest
# speedup vs baseline: 1.0094x; 1.0040x over previous
.Lnc14_okf:
.Lnc14_done:
.LBB0_1634:
	s_or_b64 exec, exec, s[0:1]
	v_readlane_b32 s0, v242, 15
	v_readlane_b32 s1, v242, 16
	s_andn2_b64 vcc, exec, s[0:1]
	s_barrier
	s_mov_b32 s96, 0
	s_cbranch_vccnz .LBB0_1667
	v_mov_b32_e32 v0, v166
	s_barrier
	v_readlane_b32 s24, v242, 41
	v_lshlrev_b32_e32 v2, 4, v0
	v_and_b32_e32 v3, 32, v0
	v_ashrrev_i32_e32 v1, 6, v0
	v_bitop3_b32 v2, v2, v3, 48 bitop3:0x6c
	v_lshlrev_b32_e32 v0, 8, v0
	v_lshrrev_b32_e32 v2, 1, v2
	v_and_b32_e32 v0, 0x3c00, v0
	v_lshlrev_b32_e32 v3, 14, v1
	v_or3_b32 v64, v3, v0, v2
	v_add_u32_e32 v0, 0x20000, v64
	v_lshlrev_b32_e32 v10, 10, v1
	v_mov_b32_e32 v1, v65
	v_lshlrev_b64 v[2:3], 1, v[64:65]
	v_readlane_b32 s25, v242, 42
	v_readfirstlane_b32 s0, v10
	v_lshlrev_b64 v[0:1], 1, v[0:1]
	v_add_u32_e32 v8, 0x2000, v10
	v_lshl_add_u64 v[4:5], s[24:25], 0, v[2:3]
	s_mov_b32 m0, s0
	v_lshl_add_u64 v[6:7], s[24:25], 0, v[0:1]
	v_readfirstlane_b32 s0, v8
	v_readlane_b32 s24, v240, 10
	v_add_u32_e32 v8, 0x4000, v10
	global_load_lds_dwordx4 v[4:5], off
	s_mov_b32 m0, s0
	v_readlane_b32 s25, v240, 11
	v_readfirstlane_b32 s0, v8
	v_add_u32_e32 v8, 0x6000, v10
	global_load_lds_dwordx4 v[6:7], off
	v_lshl_add_u64 v[2:3], s[24:25], 0, v[2:3]
	s_mov_b32 m0, s0
	v_readfirstlane_b32 s0, v8
	v_add_u32_e32 v11, 0x8000, v10
	global_load_lds_dwordx4 v[2:3], off
	v_lshl_add_u64 v[0:1], s[24:25], 0, v[0:1]
	s_mov_b32 m0, s0
	v_readfirstlane_b32 s0, v11
	v_add_u32_e32 v11, 0xa000, v10
	global_load_lds_dwordx4 v[0:1], off
	v_lshl_add_u64 v[8:9], v[4:5], 0, 64
	s_mov_b32 m0, s0
	v_readfirstlane_b32 s0, v11
	v_add_u32_e32 v11, 0xc000, v10
	global_load_lds_dwordx4 v[8:9], off
	v_lshl_add_u64 v[8:9], v[6:7], 0, 64
	s_mov_b32 m0, s0
	v_readfirstlane_b32 s0, v11
	v_add_u32_e32 v11, 0xe000, v10
	global_load_lds_dwordx4 v[8:9], off
	v_lshl_add_u64 v[8:9], v[2:3], 0, 64
	s_mov_b32 m0, s0
	v_readfirstlane_b32 s0, v11
	v_add_u32_e32 v11, 0x10000, v10
	global_load_lds_dwordx4 v[8:9], off
	v_lshl_add_u64 v[8:9], v[0:1], 0, 64
	s_mov_b32 m0, s0
	v_readfirstlane_b32 s0, v11
	v_add_u32_e32 v11, 0x12000, v10
	global_load_lds_dwordx4 v[8:9], off
	v_lshl_add_u64 v[8:9], v[4:5], 0, s[34:35]
	s_mov_b32 m0, s0
	v_readfirstlane_b32 s0, v11
	v_add_u32_e32 v11, 0x14000, v10
	global_load_lds_dwordx4 v[8:9], off
	v_lshl_add_u64 v[8:9], v[6:7], 0, s[34:35]
	s_mov_b32 m0, s0
	v_readfirstlane_b32 s0, v11
	v_add_u32_e32 v11, 0x16000, v10
	global_load_lds_dwordx4 v[8:9], off
	v_lshl_add_u64 v[8:9], v[2:3], 0, s[34:35]
	s_mov_b32 m0, s0
	v_readfirstlane_b32 s0, v11
	global_load_lds_dwordx4 v[8:9], off
	v_lshl_add_u64 v[8:9], v[0:1], 0, s[34:35]
	s_mov_b32 m0, s0
	v_lshl_add_u64 v[4:5], v[4:5], 0, s[82:83]
	global_load_lds_dwordx4 v[8:9], off
	v_add_u32_e32 v8, 0x18000, v10
	v_lshl_add_u64 v[2:3], v[2:3], 0, s[82:83]
	v_readfirstlane_b32 s0, v8
	s_mov_b32 m0, s0
	v_lshl_add_u64 v[0:1], v[0:1], 0, s[82:83]
	global_load_lds_dwordx4 v[4:5], off
	v_lshl_add_u64 v[4:5], v[6:7], 0, s[82:83]
	v_add_u32_e32 v6, 0x1a000, v10
	s_mov_b32 s64, 1
	v_readfirstlane_b32 s0, v6
	s_mov_b32 m0, s0
	s_mov_b32 s65, 0
	global_load_lds_dwordx4 v[4:5], off
	v_add_u32_e32 v4, 0x1c000, v10
	v_readlane_b32 s28, v242, 39
	v_readfirstlane_b32 s0, v4
	s_mov_b32 m0, s0
	v_readlane_b32 s30, v242, 45
	global_load_lds_dwordx4 v[2:3], off
	v_add_u32_e32 v2, 0x1e000, v10
	v_readlane_b32 s46, v240, 8
	v_readfirstlane_b32 s0, v2
	s_mov_b32 m0, s0
	v_readlane_b32 s29, v242, 40
	global_load_lds_dwordx4 v[0:1], off
	v_readlane_b32 s31, v242, 46
	s_waitcnt vmcnt(0)
	s_branch .LBB0_1637

.Lf3_j:
	v_add_f32_e32 v132, v210, v211
	v_add_f32_e32 v133, v212, v213
	v_add_f32_e32 v132, v132, v133
	v_mov_b32_e32 v133, v132
	v_mov_b32_e32 v134, v132
	s_nop 1
	v_permlane32_swap_b32_e32 v133, v134
	v_add_f32_e32 v132, v133, v134
	v_mov_b32_e32 v133, v132
	v_mov_b32_e32 v134, v132
	s_nop 1
	v_permlane16_swap_b32_e32 v133, v134
	v_add_f32_e32 v132, v133, v134
	v_fmaak_f32 v133, v132, v130, 0x3727c5ac
	v_rsq_f32_e32 v134, v133
	v_mul_f32_e32 v133, 0.5, v133
	s_nop 0
	v_mul_f32_e32 v132, v133, v134
	v_fma_f32 v132, -v132, v134, 0.5
	v_fma_f32 v136, v134, v132, v134
	v_mov_b32_e32 v137, v136
	v_pk_mul_f32 v[126:127], v[126:127], v[136:137]
	v_pk_mul_f32 v[128:129], v[128:129], v[136:137]
	v_pk_mul_f32 v[122:123], v[122:123], v[136:137]
	v_pk_mul_f32 v[124:125], v[124:125], v[136:137]
	v_pk_mul_f32 v[118:119], v[118:119], v[136:137]
	v_pk_mul_f32 v[120:121], v[120:121], v[136:137]
	v_pk_mul_f32 v[114:115], v[114:115], v[136:137]
	v_pk_mul_f32 v[116:117], v[116:117], v[136:137]
	v_cvt_pk_bf16_f32 v126, v126, v127
	v_cvt_pk_bf16_f32 v127, v128, v129
	v_cvt_pk_bf16_f32 v128, v122, v123
	v_cvt_pk_bf16_f32 v129, v124, v125
	v_cvt_pk_bf16_f32 v118, v118, v119
	v_cvt_pk_bf16_f32 v119, v120, v121
	v_cvt_pk_bf16_f32 v120, v114, v115
	v_cvt_pk_bf16_f32 v121, v116, v117
	s_nop 1
	v_permlane16_swap_b32_e32 v126, v128
	v_permlane16_swap_b32_e32 v127, v129
	v_permlane16_swap_b32_e32 v118, v120
	v_permlane16_swap_b32_e32 v119, v121
	global_store_dwordx4 v[246:247], v[126:129], off
	global_store_dwordx4 v[246:247], v[118:121], off offset:64
	v_add_co_u32_e32 v246, vcc, 0x2c000, v246
	s_nop 1
	v_addc_co_u32_e32 v247, vcc, 0, v247, vcc
	s_waitcnt vmcnt(8)
	v_add_f32_e32 v132, v214, v215
	v_add_f32_e32 v133, v216, v217
	v_add_f32_e32 v132, v132, v133
	v_mov_b32_e32 v133, v132
	v_mov_b32_e32 v134, v132
	s_nop 1
	v_permlane32_swap_b32_e32 v133, v134
	v_add_f32_e32 v132, v133, v134
	v_mov_b32_e32 v133, v132
	v_mov_b32_e32 v134, v132
	s_nop 1
	v_permlane16_swap_b32_e32 v133, v134
	v_add_f32_e32 v132, v133, v134
	v_fmaak_f32 v133, v132, v130, 0x3727c5ac
	v_rsq_f32_e32 v134, v133
	v_mul_f32_e32 v133, 0.5, v133
	s_nop 0
	v_mul_f32_e32 v132, v133, v134
	v_fma_f32 v132, -v132, v134, 0.5
	v_fma_f32 v136, v134, v132, v134
	v_mov_b32_e32 v137, v136
	v_pk_mul_f32 v[110:111], v[110:111], v[136:137]
	v_pk_mul_f32 v[112:113], v[112:113], v[136:137]
	v_pk_mul_f32 v[106:107], v[106:107], v[136:137]
	v_pk_mul_f32 v[108:109], v[108:109], v[136:137]
	v_pk_mul_f32 v[102:103], v[102:103], v[136:137]
	v_pk_mul_f32 v[104:105], v[104:105], v[136:137]
	v_pk_mul_f32 v[98:99], v[98:99], v[136:137]
	v_pk_mul_f32 v[100:101], v[100:101], v[136:137]
	v_cvt_pk_bf16_f32 v110, v110, v111
	v_cvt_pk_bf16_f32 v111, v112, v113
	v_cvt_pk_bf16_f32 v112, v106, v107
	v_cvt_pk_bf16_f32 v113, v108, v109
	v_cvt_pk_bf16_f32 v102, v102, v103
	v_cvt_pk_bf16_f32 v103, v104, v105
	v_cvt_pk_bf16_f32 v104, v98, v99
	v_cvt_pk_bf16_f32 v105, v100, v101
	s_nop 1
	v_permlane16_swap_b32_e32 v110, v112
	v_permlane16_swap_b32_e32 v111, v113
	v_permlane16_swap_b32_e32 v102, v104
	v_permlane16_swap_b32_e32 v103, v105
	global_store_dwordx4 v[246:247], v[110:113], off
	global_store_dwordx4 v[246:247], v[102:105], off offset:64
	v_add_co_u32_e32 v246, vcc, 0x2c000, v246
	s_nop 1
	v_addc_co_u32_e32 v247, vcc, 0, v247, vcc
	s_waitcnt vmcnt(9)
	v_add_f32_e32 v132, v218, v219
	v_add_f32_e32 v133, v220, v221
	v_add_f32_e32 v132, v132, v133
	v_mov_b32_e32 v133, v132
	v_mov_b32_e32 v134, v132
	s_nop 1
	v_permlane32_swap_b32_e32 v133, v134
	v_add_f32_e32 v132, v133, v134
	v_mov_b32_e32 v133, v132
	v_mov_b32_e32 v134, v132
	s_nop 1
	v_permlane16_swap_b32_e32 v133, v134
	v_add_f32_e32 v132, v133, v134
	v_fmaak_f32 v133, v132, v130, 0x3727c5ac
	v_rsq_f32_e32 v134, v133
	v_mul_f32_e32 v133, 0.5, v133
	s_nop 0
	v_mul_f32_e32 v132, v133, v134
	v_fma_f32 v132, -v132, v134, 0.5
	v_fma_f32 v136, v134, v132, v134
	v_mov_b32_e32 v137, v136
	v_pk_mul_f32 v[94:95], v[94:95], v[136:137]
	v_pk_mul_f32 v[96:97], v[96:97], v[136:137]
	v_pk_mul_f32 v[90:91], v[90:91], v[136:137]
	v_pk_mul_f32 v[92:93], v[92:93], v[136:137]
	v_pk_mul_f32 v[86:87], v[86:87], v[136:137]
	v_pk_mul_f32 v[88:89], v[88:89], v[136:137]
	v_pk_mul_f32 v[82:83], v[82:83], v[136:137]
	v_pk_mul_f32 v[84:85], v[84:85], v[136:137]
	v_cvt_pk_bf16_f32 v94, v94, v95
	v_cvt_pk_bf16_f32 v95, v96, v97
	v_cvt_pk_bf16_f32 v96, v90, v91
	v_cvt_pk_bf16_f32 v97, v92, v93
	v_cvt_pk_bf16_f32 v86, v86, v87
	v_cvt_pk_bf16_f32 v87, v88, v89
	v_cvt_pk_bf16_f32 v88, v82, v83
	v_cvt_pk_bf16_f32 v89, v84, v85
	s_nop 1
	v_permlane16_swap_b32_e32 v94, v96
	v_permlane16_swap_b32_e32 v95, v97
	v_permlane16_swap_b32_e32 v86, v88
	v_permlane16_swap_b32_e32 v87, v89
	global_store_dwordx4 v[246:247], v[94:97], off
	global_store_dwordx4 v[246:247], v[86:89], off offset:64
	v_add_co_u32_e32 v246, vcc, 0x2c000, v246
	s_nop 1
	v_addc_co_u32_e32 v247, vcc, 0, v247, vcc
	s_waitcnt vmcnt(10)
	v_add_f32_e32 v132, v222, v223
	v_add_f32_e32 v133, v224, v225
	v_add_f32_e32 v132, v132, v133
	v_mov_b32_e32 v133, v132
	v_mov_b32_e32 v134, v132
	s_nop 1
	v_permlane32_swap_b32_e32 v133, v134
	v_add_f32_e32 v132, v133, v134
	v_mov_b32_e32 v133, v132
	v_mov_b32_e32 v134, v132
	s_nop 1
	v_permlane16_swap_b32_e32 v133, v134
	v_add_f32_e32 v132, v133, v134
	v_fmaak_f32 v133, v132, v130, 0x3727c5ac
	v_rsq_f32_e32 v134, v133
	v_mul_f32_e32 v133, 0.5, v133
	s_nop 0
	v_mul_f32_e32 v132, v133, v134
	v_fma_f32 v132, -v132, v134, 0.5
	v_fma_f32 v136, v134, v132, v134
	v_mov_b32_e32 v137, v136
	v_pk_mul_f32 v[78:79], v[78:79], v[136:137]
	v_pk_mul_f32 v[80:81], v[80:81], v[136:137]
	v_pk_mul_f32 v[74:75], v[74:75], v[136:137]
	v_pk_mul_f32 v[76:77], v[76:77], v[136:137]
	v_pk_mul_f32 v[70:71], v[70:71], v[136:137]
	v_pk_mul_f32 v[72:73], v[72:73], v[136:137]
	v_pk_mul_f32 v[66:67], v[66:67], v[136:137]
	v_pk_mul_f32 v[68:69], v[68:69], v[136:137]
	v_cvt_pk_bf16_f32 v78, v78, v79
	v_cvt_pk_bf16_f32 v79, v80, v81
	v_cvt_pk_bf16_f32 v80, v74, v75
	v_cvt_pk_bf16_f32 v81, v76, v77
	v_cvt_pk_bf16_f32 v70, v70, v71
	v_cvt_pk_bf16_f32 v71, v72, v73
	v_cvt_pk_bf16_f32 v72, v66, v67
	v_cvt_pk_bf16_f32 v73, v68, v69
	s_nop 1
	v_permlane16_swap_b32_e32 v78, v80
	v_permlane16_swap_b32_e32 v79, v81
	v_permlane16_swap_b32_e32 v70, v72
	v_permlane16_swap_b32_e32 v71, v73
	global_store_dwordx4 v[246:247], v[78:81], off
	global_store_dwordx4 v[246:247], v[70:73], off offset:64
	v_add_co_u32_e32 v246, vcc, 0x2c000, v246
	s_nop 1
	v_addc_co_u32_e32 v247, vcc, 0, v247, vcc
	s_waitcnt vmcnt(11)
	v_add_f32_e32 v132, v226, v227
	v_add_f32_e32 v133, v228, v229
	v_add_f32_e32 v132, v132, v133
	v_mov_b32_e32 v133, v132
	v_mov_b32_e32 v134, v132
	s_nop 1
	v_permlane32_swap_b32_e32 v133, v134
	v_add_f32_e32 v132, v133, v134
	v_mov_b32_e32 v133, v132
	v_mov_b32_e32 v134, v132
	s_nop 1
	v_permlane16_swap_b32_e32 v133, v134
	v_add_f32_e32 v132, v133, v134
	v_fmaak_f32 v133, v132, v130, 0x3727c5ac
	v_rsq_f32_e32 v134, v133
	v_mul_f32_e32 v133, 0.5, v133
	s_nop 0
	v_mul_f32_e32 v132, v133, v134
	v_fma_f32 v132, -v132, v134, 0.5
	v_fma_f32 v136, v134, v132, v134
	v_mov_b32_e32 v137, v136
	v_pk_mul_f32 v[60:61], v[60:61], v[136:137]
	v_pk_mul_f32 v[62:63], v[62:63], v[136:137]
	v_pk_mul_f32 v[56:57], v[56:57], v[136:137]
	v_pk_mul_f32 v[58:59], v[58:59], v[136:137]
	v_pk_mul_f32 v[52:53], v[52:53], v[136:137]
	v_pk_mul_f32 v[54:55], v[54:55], v[136:137]
	v_pk_mul_f32 v[48:49], v[48:49], v[136:137]
	v_pk_mul_f32 v[50:51], v[50:51], v[136:137]
	v_cvt_pk_bf16_f32 v60, v60, v61
	v_cvt_pk_bf16_f32 v61, v62, v63
	v_cvt_pk_bf16_f32 v62, v56, v57
	v_cvt_pk_bf16_f32 v63, v58, v59
	v_cvt_pk_bf16_f32 v52, v52, v53
	v_cvt_pk_bf16_f32 v53, v54, v55
	v_cvt_pk_bf16_f32 v54, v48, v49
	v_cvt_pk_bf16_f32 v55, v50, v51
	s_nop 1
	v_permlane16_swap_b32_e32 v60, v62
	v_permlane16_swap_b32_e32 v61, v63
	v_permlane16_swap_b32_e32 v52, v54
	v_permlane16_swap_b32_e32 v53, v55
	global_store_dwordx4 v[246:247], v[60:63], off
	global_store_dwordx4 v[246:247], v[52:55], off offset:64
	v_add_co_u32_e32 v246, vcc, 0x2c000, v246
	s_nop 1
	v_addc_co_u32_e32 v247, vcc, 0, v247, vcc
	s_waitcnt vmcnt(12)
	v_add_f32_e32 v132, v230, v231
	v_add_f32_e32 v133, v232, v233
	v_add_f32_e32 v132, v132, v133
	v_mov_b32_e32 v133, v132
	v_mov_b32_e32 v134, v132
	s_nop 1
	v_permlane32_swap_b32_e32 v133, v134
	v_add_f32_e32 v132, v133, v134
	v_mov_b32_e32 v133, v132
	v_mov_b32_e32 v134, v132
	s_nop 1
	v_permlane16_swap_b32_e32 v133, v134
	v_add_f32_e32 v132, v133, v134
	v_fmaak_f32 v133, v132, v130, 0x3727c5ac
	v_rsq_f32_e32 v134, v133
	v_mul_f32_e32 v133, 0.5, v133
	s_nop 0
	v_mul_f32_e32 v132, v133, v134
	v_fma_f32 v132, -v132, v134, 0.5
	v_fma_f32 v136, v134, v132, v134
	v_mov_b32_e32 v137, v136
	v_pk_mul_f32 v[44:45], v[44:45], v[136:137]
	v_pk_mul_f32 v[46:47], v[46:47], v[136:137]
	v_pk_mul_f32 v[40:41], v[40:41], v[136:137]
	v_pk_mul_f32 v[42:43], v[42:43], v[136:137]
	v_pk_mul_f32 v[36:37], v[36:37], v[136:137]
	v_pk_mul_f32 v[38:39], v[38:39], v[136:137]
	v_pk_mul_f32 v[32:33], v[32:33], v[136:137]
	v_pk_mul_f32 v[34:35], v[34:35], v[136:137]
	v_cvt_pk_bf16_f32 v44, v44, v45
	v_cvt_pk_bf16_f32 v45, v46, v47
	v_cvt_pk_bf16_f32 v46, v40, v41
	v_cvt_pk_bf16_f32 v47, v42, v43
	v_cvt_pk_bf16_f32 v36, v36, v37
	v_cvt_pk_bf16_f32 v37, v38, v39
	v_cvt_pk_bf16_f32 v38, v32, v33
	v_cvt_pk_bf16_f32 v39, v34, v35
	s_nop 1
	v_permlane16_swap_b32_e32 v44, v46
	v_permlane16_swap_b32_e32 v45, v47
	v_permlane16_swap_b32_e32 v36, v38
	v_permlane16_swap_b32_e32 v37, v39
	global_store_dwordx4 v[246:247], v[44:47], off
	global_store_dwordx4 v[246:247], v[36:39], off offset:64
	v_add_co_u32_e32 v246, vcc, 0x2c000, v246
	s_nop 1
	v_addc_co_u32_e32 v247, vcc, 0, v247, vcc
	s_waitcnt vmcnt(13)
	v_add_f32_e32 v132, v234, v235
	v_add_f32_e32 v133, v236, v237
	v_add_f32_e32 v132, v132, v133
	v_mov_b32_e32 v133, v132
	v_mov_b32_e32 v134, v132
	s_nop 1
	v_permlane32_swap_b32_e32 v133, v134
	v_add_f32_e32 v132, v133, v134
	v_mov_b32_e32 v133, v132
	v_mov_b32_e32 v134, v132
	s_nop 1
	v_permlane16_swap_b32_e32 v133, v134
	v_add_f32_e32 v132, v133, v134
	v_fmaak_f32 v133, v132, v130, 0x3727c5ac
	v_rsq_f32_e32 v134, v133
	v_mul_f32_e32 v133, 0.5, v133
	s_nop 0
	v_mul_f32_e32 v132, v133, v134
	v_fma_f32 v132, -v132, v134, 0.5
	v_fma_f32 v136, v134, v132, v134
	v_mov_b32_e32 v137, v136
	v_pk_mul_f32 v[28:29], v[28:29], v[136:137]
	v_pk_mul_f32 v[30:31], v[30:31], v[136:137]
	v_pk_mul_f32 v[24:25], v[24:25], v[136:137]
	v_pk_mul_f32 v[26:27], v[26:27], v[136:137]
	v_pk_mul_f32 v[20:21], v[20:21], v[136:137]
	v_pk_mul_f32 v[22:23], v[22:23], v[136:137]
	v_pk_mul_f32 v[16:17], v[16:17], v[136:137]
	v_pk_mul_f32 v[18:19], v[18:19], v[136:137]
	v_cvt_pk_bf16_f32 v28, v28, v29
	v_cvt_pk_bf16_f32 v29, v30, v31
	v_cvt_pk_bf16_f32 v30, v24, v25
	v_cvt_pk_bf16_f32 v31, v26, v27
	v_cvt_pk_bf16_f32 v20, v20, v21
	v_cvt_pk_bf16_f32 v21, v22, v23
	v_cvt_pk_bf16_f32 v22, v16, v17
	v_cvt_pk_bf16_f32 v23, v18, v19
	s_nop 1
	v_permlane16_swap_b32_e32 v28, v30
	v_permlane16_swap_b32_e32 v29, v31
	v_permlane16_swap_b32_e32 v20, v22
	v_permlane16_swap_b32_e32 v21, v23
	global_store_dwordx4 v[246:247], v[28:31], off
	global_store_dwordx4 v[246:247], v[20:23], off offset:64
	v_add_co_u32_e32 v246, vcc, 0x2c000, v246
	s_nop 1
	v_addc_co_u32_e32 v247, vcc, 0, v247, vcc
	s_waitcnt vmcnt(14)
	v_add_f32_e32 v132, v252, v253
	v_add_f32_e32 v133, v254, v255
	v_add_f32_e32 v132, v132, v133
	v_mov_b32_e32 v133, v132
	v_mov_b32_e32 v134, v132
	s_nop 1
	v_permlane32_swap_b32_e32 v133, v134
	v_add_f32_e32 v132, v133, v134
	v_mov_b32_e32 v133, v132
	v_mov_b32_e32 v134, v132
	s_nop 1
	v_permlane16_swap_b32_e32 v133, v134
	v_add_f32_e32 v132, v133, v134
	v_fmaak_f32 v133, v132, v130, 0x3727c5ac
	v_rsq_f32_e32 v134, v133
	v_mul_f32_e32 v133, 0.5, v133
	s_nop 0
	v_mul_f32_e32 v132, v133, v134
	v_fma_f32 v132, -v132, v134, 0.5
	v_fma_f32 v136, v134, v132, v134
	v_mov_b32_e32 v137, v136
	v_pk_mul_f32 v[12:13], v[12:13], v[136:137]
	v_pk_mul_f32 v[14:15], v[14:15], v[136:137]
	v_pk_mul_f32 v[8:9], v[8:9], v[136:137]
	v_pk_mul_f32 v[10:11], v[10:11], v[136:137]
	v_pk_mul_f32 v[4:5], v[4:5], v[136:137]
	v_pk_mul_f32 v[6:7], v[6:7], v[136:137]
	v_pk_mul_f32 v[0:1], v[0:1], v[136:137]
	v_pk_mul_f32 v[2:3], v[2:3], v[136:137]
	v_cvt_pk_bf16_f32 v12, v12, v13
	v_cvt_pk_bf16_f32 v13, v14, v15
	v_cvt_pk_bf16_f32 v14, v8, v9
	v_cvt_pk_bf16_f32 v15, v10, v11
	v_cvt_pk_bf16_f32 v4, v4, v5
	v_cvt_pk_bf16_f32 v5, v6, v7
	v_cvt_pk_bf16_f32 v6, v0, v1
	v_cvt_pk_bf16_f32 v7, v2, v3
	s_nop 1
	v_permlane16_swap_b32_e32 v12, v14
	v_permlane16_swap_b32_e32 v13, v15
	v_permlane16_swap_b32_e32 v4, v6
	v_permlane16_swap_b32_e32 v5, v7
	global_store_dwordx4 v[246:247], v[12:15], off
	global_store_dwordx4 v[246:247], v[4:7], off offset:64
	s_cmp_eq_u32 s64, 6
	s_cbranch_scc0 .Lmb_skip
	s_cmp_eq_u32 s94, 0x100
	s_cbranch_scc0 .Lmb_skip
	v_writelane_b32 v240, s0, 40
	v_writelane_b32 v240, s1, 41
	v_writelane_b32 v240, s24, 42
	v_writelane_b32 v240, s25, 43
	v_writelane_b32 v240, s26, 44
	v_writelane_b32 v240, s27, 45
	v_writelane_b32 v240, s28, 46
	v_writelane_b32 v240, s29, 47
	s_waitcnt vmcnt(0) lgkmcnt(0)
	s_barrier
	v_readlane_b32 s28, v241, 17
	v_readlane_b32 s29, v241, 18
	s_nop 3
	s_and_saveexec_b64 s[0:1], s[28:29]
	s_cbranch_execz .Lmb_end
	s_waitcnt vmcnt(0) lgkmcnt(0)
	v_readlane_b32 s26, v240, 63
	v_readlane_b32 s27, v240, 61
	v_readlane_b32 s28, v240, 62
	s_add_u32 s24, s92, 0xb500900
	s_addc_u32 s25, s93, 0
	s_add_i32 s26, s26, 1
	s_nop 1
	v_writelane_b32 v240, s26, 63
	v_mov_b32_e32 v0, s27
	v_lshlrev_b32_e32 v0, 7, v0
	v_lshl_add_u32 v0, s28, 2, v0
	v_add_u32_e32 v0, 0x1400, v0
	v_mov_b32_e32 v1, s26
	global_store_dword v0, v1, s[24:25]
	s_cmp_lg_u32 s28, 0
	s_cbranch_scc1 .Lnc18_f
	buffer_inv sc1
	v_readlane_b32 s29, v240, 60
	s_mov_b32 exec_lo, -1
	s_mov_b32 exec_hi, 0
	v_mbcnt_lo_u32_b32 v2, -1, 0
	s_cmp_lg_u32 s29, 0
	s_cbranch_scc1 .Lnc18_have
	v_lshlrev_b32_e32 v3, 8, v2
	v_add_u32_e32 v3, 0x400, v3
	global_load_dword v4, v3, s[24:25] sc0 sc1
	s_waitcnt vmcnt(0)
	v_readlane_b32 s29, v4, s27
	v_cmp_ne_u32_e32 vcc, 0, v4
	s_nop 3
	s_and_b32 s28, vcc_lo, 0xffff
	v_writelane_b32 v240, s29, 60
	v_writelane_b32 v240, s28, 59

.Lnc18_okf:
.Lnc18_done:
.Lmb_end:
	s_or_b64 exec, exec, s[0:1]
	s_barrier
	v_readlane_b32 s0, v240, 40
	v_readlane_b32 s1, v240, 41
	v_readlane_b32 s24, v240, 42
	v_readlane_b32 s25, v240, 43
	v_readlane_b32 s26, v240, 44
	v_readlane_b32 s27, v240, 45
	v_readlane_b32 s28, v240, 46
	v_readlane_b32 s29, v240, 47
	s_nop 3
.Lmb_skip:
	s_andn2_b64 vcc, exec, s[26:27]
	s_cbranch_vccz .LBB0_1666

.LBB0_1666:
	s_movk_i32 s46, 0x3fff
	s_mov_b32 s96, 0
	s_cmp_eq_u32 s94, 0x100
	s_cbranch_scc0 .Lcvm_done
	s_mov_b32 s96, 2
	s_cmp_eq_u32 s64, 6
	s_cbranch_scc0 .Lcvm_done
	s_mov_b32 s96, 1
	s_waitcnt vmcnt(0)
	s_branch .LBB0_1720
.Lcvm_done:
.LBB0_1667:
	s_waitcnt vmcnt(0)
	s_waitcnt vmcnt(0) lgkmcnt(0)
	s_barrier
	s_and_saveexec_b64 s[0:1], s[74:75]
	s_cbranch_execz .LBB0_1720
	s_waitcnt vmcnt(0) lgkmcnt(0)
	v_readlane_b32 s26, v240, 63
	v_readlane_b32 s27, v240, 61
	v_readlane_b32 s28, v240, 62
	s_add_u32 s24, s92, 0xb500900
	s_addc_u32 s25, s93, 0
	s_add_i32 s26, s26, 1
	s_nop 1
	v_writelane_b32 v240, s26, 63
	v_mov_b32_e32 v0, s27
	v_lshlrev_b32_e32 v0, 7, v0
	v_lshl_add_u32 v0, s28, 2, v0
	v_add_u32_e32 v0, 0x1400, v0
	v_mov_b32_e32 v1, s26
	global_store_dword v0, v1, s[24:25]
	s_cmp_lg_u32 s28, 0
	s_cbranch_scc1 .Lnc15_f
	buffer_inv sc1
	v_readlane_b32 s29, v240, 60
	s_mov_b32 exec_lo, -1
	s_mov_b32 exec_hi, 0
	v_mbcnt_lo_u32_b32 v2, -1, 0
	s_cmp_lg_u32 s29, 0
	s_cbranch_scc1 .Lnc15_have
	v_lshlrev_b32_e32 v3, 8, v2
	v_add_u32_e32 v3, 0x400, v3
	global_load_dword v4, v3, s[24:25] sc0 sc1
	s_waitcnt vmcnt(0)
	v_readlane_b32 s29, v4, s27
	v_cmp_ne_u32_e32 vcc, 0, v4
	s_nop 3
	s_and_b32 s28, vcc_lo, 0xffff
	v_writelane_b32 v240, s29, 60
	v_writelane_b32 v240, s28, 59

.Lnc15_okf:
.Lnc15_done:
.LBB0_1720:
	s_or_b64 exec, exec, s[0:1]
	v_mov_b32_e32 v0, v166
	v_readlane_b32 s0, v244, 2
	s_cmp_eq_u32 s94, 0x100
	s_cbranch_scc0 .Lcv_keep
	v_readlane_b32 s0, v241, 19
	s_nop 3
	s_and_b32 s1, s0, 7
	s_lshl_b32 s1, s1, 5
	s_lshr_b32 s0, s0, 3
	s_add_u32 s0, s0, s1
	s_lshl_b32 s0, s0, 9
	s_cmp_eq_u32 s96, 1
	s_cbranch_scc0 .Lcv_m2
	s_sub_u32 s0, s0, 0x10000
	s_branch .Lcv_keep
.Lcv_m2:
	s_cmp_eq_u32 s96, 2
	s_cbranch_scc0 .Lcv_keep
	s_add_u32 s0, s0, 0x34000
.Lcv_keep:
	s_barrier
	s_nop 0
	v_add_u32_e32 v64, s0, v0
	s_mov_b32 s0, 0xb0000
	s_cmp_eq_u32 s96, 1
	s_cselect_b32 s0, 0x34000, s0
	v_cmp_gt_i32_e32 vcc, s0, v64
	s_and_saveexec_b64 s[24:25], vcc
	s_cbranch_execz .LBB0_1727
	s_mov_b64 s[28:29], 0
	s_branch .LBB0_1723
.LBB0_1722:
	s_or_b64 exec, exec, s[26:27]
	v_mov_b64_e32 v[36:37], s[18:19]
	s_movk_i32 s27, 0x2c00
	v_mad_i64_i32 v[2:3], s[0:1], v152, s27, v[36:37]
	v_lshlrev_b64 v[146:147], 1, v[0:1]
	v_lshl_add_u64 v[2:3], v[2:3], 0, v[146:147]
	s_movk_i32 s26, 0x1000
	v_add_co_u32_e32 v4, vcc, s26, v2
	v_or_b32_e32 v201, 1, v152
	s_nop 0
	v_addc_co_u32_e32 v5, vcc, 0, v3, vcc
	global_load_dwordx4 v[142:145], v[2:3], off
	global_load_dwordx4 v[138:141], v[4:5], off offset:1536
	v_mad_i64_i32 v[2:3], s[0:1], v201, s27, v[36:37]
	v_lshl_add_u64 v[2:3], v[2:3], 0, v[146:147]
	v_add_co_u32_e32 v4, vcc, s26, v2
	v_or_b32_e32 v199, 2, v152
	s_nop 0
	v_addc_co_u32_e32 v5, vcc, 0, v3, vcc
	global_load_dwordx4 v[114:117], v[2:3], off
	global_load_dwordx4 v[106:109], v[4:5], off offset:1536
	v_mad_i64_i32 v[2:3], s[0:1], v199, s27, v[36:37]
	v_readlane_b32 s0, v241, 58
	v_lshlrev_b64 v[14:15], 2, v[0:1]
	v_readlane_b32 s1, v241, 59
	v_lshl_add_u64 v[12:13], v[2:3], 0, v[146:147]
	v_add_co_u32_e32 v38, vcc, s26, v12
	v_lshl_add_u64 v[4:5], s[0:1], 0, v[14:15]
	v_readlane_b32 s0, v241, 50
	v_readlane_b32 s1, v241, 51
	v_addc_co_u32_e32 v39, vcc, 0, v13, vcc
	s_nop 0
	v_lshl_add_u64 v[16:17], s[0:1], 0, v[14:15]
	v_readlane_b32 s0, v241, 52
	v_readlane_b32 s1, v241, 53
	s_waitcnt vmcnt(5)
	v_lshlrev_b32_e32 v148, 16, v130
	v_and_b32_e32 v149, 0xffff0000, v130
	v_lshl_add_u64 v[18:19], s[0:1], 0, v[14:15]
	v_readlane_b32 s0, v241, 24
	v_readlane_b32 s1, v241, 25
	v_lshlrev_b32_e32 v158, 16, v134
	v_and_b32_e32 v159, 0xffff0000, v134
	v_lshl_add_u64 v[8:9], s[0:1], 0, v[14:15]
	v_readlane_b32 s0, v241, 48
	v_readlane_b32 s1, v241, 49
	s_waitcnt vmcnt(4)
	v_lshlrev_b32_e32 v162, 16, v122
	v_and_b32_e32 v163, 0xffff0000, v122
	v_lshl_add_u64 v[24:25], s[0:1], 0, v[14:15]
	v_readlane_b32 s0, v241, 56
	v_readlane_b32 s1, v241, 57
	global_load_dwordx4 v[0:3], v[4:5], off offset:16
	global_load_dwordx4 v[32:35], v[4:5], off
	s_nop 0
	global_load_dwordx4 v[4:7], v[8:9], off offset:16
	global_load_dwordx4 v[40:43], v[8:9], off
	s_nop 0
	global_load_dwordx4 v[8:11], v[16:17], off offset:16
	global_load_dwordx4 v[44:47], v[16:17], off
	global_load_dwordx4 v[20:23], v[24:25], off offset:16
	global_load_dwordx4 v[56:59], v[24:25], off
	s_nop 0
	global_load_dwordx4 v[24:27], v[18:19], off offset:16
	global_load_dwordx4 v[66:69], v[18:19], off
	v_lshl_add_u64 v[16:17], s[0:1], 0, v[14:15]
	global_load_dwordx4 v[28:31], v[16:17], off offset:16
	global_load_dwordx4 v[70:73], v[16:17], off
	v_readlane_b32 s0, v241, 54
	v_readlane_b32 s1, v241, 55
	v_lshlrev_b32_e32 v150, 16, v126
	v_and_b32_e32 v151, 0xffff0000, v126
	v_lshl_add_u64 v[48:49], s[0:1], 0, v[14:15]
	global_load_dwordx4 v[16:19], v[48:49], off offset:16
	global_load_dwordx4 v[52:55], v[48:49], off
	global_load_dwordx4 v[118:121], v[12:13], off
	global_load_dwordx4 v[110:113], v[38:39], off offset:1536
	v_lshl_add_u64 v[38:39], s[70:71], 0, v[14:15]
	global_load_dwordx4 v[12:15], v[38:39], off offset:16
	global_load_dwordx4 v[48:51], v[38:39], off
	v_lshlrev_b32_e32 v130, 16, v131
	v_and_b32_e32 v131, 0xffff0000, v131
	v_lshlrev_b32_e32 v206, 16, v124
	v_and_b32_e32 v207, 0xffff0000, v124
	v_or_b32_e32 v200, 3, v152
	v_mad_i64_i32 v[38:39], s[0:1], v200, s27, v[36:37]
	v_lshl_add_u64 v[38:39], v[38:39], 0, v[146:147]
	v_add_co_u32_e32 v60, vcc, s26, v38
	v_or_b32_e32 v198, 4, v152
	s_nop 0
	v_addc_co_u32_e32 v61, vcc, 0, v39, vcc
	global_load_dwordx4 v[102:105], v[38:39], off
	global_load_dwordx4 v[98:101], v[60:61], off offset:1536
	v_mad_i64_i32 v[38:39], s[0:1], v198, s27, v[36:37]
	v_lshl_add_u64 v[38:39], v[38:39], 0, v[146:147]
	v_add_co_u32_e32 v60, vcc, s26, v38
	v_or_b32_e32 v197, 5, v152
	s_nop 0
	v_addc_co_u32_e32 v61, vcc, 0, v39, vcc
	global_load_dwordx4 v[94:97], v[38:39], off
	global_load_dwordx4 v[90:93], v[60:61], off offset:1536
	v_mad_i64_i32 v[38:39], s[0:1], v197, s27, v[36:37]
	v_lshl_add_u64 v[38:39], v[38:39], 0, v[146:147]
	v_add_co_u32_e32 v60, vcc, s26, v38
	v_or_b32_e32 v165, 6, v152
	s_nop 0
	v_addc_co_u32_e32 v61, vcc, 0, v39, vcc
	global_load_dwordx4 v[86:89], v[38:39], off
	global_load_dwordx4 v[82:85], v[60:61], off offset:1536
	v_mad_i64_i32 v[38:39], s[0:1], v165, s27, v[36:37]
	v_lshl_add_u64 v[38:39], v[38:39], 0, v[146:147]
	v_or_b32_e32 v164, 7, v152
	v_add_co_u32_e32 v60, vcc, s26, v38
	v_mad_i64_i32 v[36:37], s[0:1], v164, s27, v[36:37]
	s_nop 0
	v_addc_co_u32_e32 v61, vcc, 0, v39, vcc
	v_readlane_b32 s0, v242, 49
	global_load_dwordx4 v[78:81], v[38:39], off
	global_load_dwordx4 v[74:77], v[60:61], off offset:1536
	v_lshl_add_u64 v[60:61], v[36:37], 0, v[146:147]
	v_readlane_b32 s1, v242, 50
	v_add_co_u32_e32 v36, vcc, s26, v60
	s_nop 0
	v_lshl_add_u64 v[146:147], s[0:1], 0, v[146:147]
	s_movk_i32 s26, 0x1600
	v_addc_co_u32_e32 v37, vcc, 0, v61, vcc
	global_load_dwordx4 v[36:39], v[36:37], off offset:1536
	s_nop 0
	global_load_dwordx4 v[60:63], v[60:61], off
	s_waitcnt vmcnt(28)
	v_and_b32_e32 v153, 0xffff0000, v109
	s_movk_i32 s23, 0x2c00
	s_waitcnt vmcnt(24)
	v_pk_fma_f32 v[148:149], v[32:33], v[148:149], v[40:41]
	v_pk_fma_f32 v[130:131], v[34:35], v[130:131], v[42:43]
	s_waitcnt vmcnt(20)
	v_pk_fma_f32 v[150:151], v[44:45], v[150:151], v[56:57]
	s_waitcnt vmcnt(18)
	v_pk_fma_f32 v[160:161], v[66:67], v[158:159], v[148:149]
	v_lshlrev_b32_e32 v148, 16, v142
	v_and_b32_e32 v149, 0xffff0000, v142
	s_waitcnt vmcnt(16)
	v_pk_fma_f32 v[160:161], v[70:71], v[148:149], v[160:161]
	s_waitcnt vmcnt(14)
	v_pk_fma_f32 v[202:203], v[52:53], v[162:163], v[150:151]
	v_mul_f32_e32 v122, 0xbfb8aa3b, v160
	v_exp_f32_e32 v122, v122
	v_mul_f32_e32 v126, 0xbfb8aa3b, v161
	v_exp_f32_e32 v126, v126
	v_lshlrev_b32_e32 v150, 16, v138
	v_add_f32_e32 v122, 1.0, v122
	v_rcp_f32_e32 v204, v122
	v_add_f32_e32 v122, 1.0, v126
	v_rcp_f32_e32 v205, v122
	v_and_b32_e32 v151, 0xffff0000, v138
	s_waitcnt vmcnt(10)
	v_pk_fma_f32 v[202:203], v[48:49], v[150:151], v[202:203]
	v_lshlrev_b32_e32 v122, 16, v143
	v_pk_mul_f32 v[160:161], v[160:161], v[204:205]
	v_lshlrev_b32_e32 v126, 16, v127
	v_pk_mul_f32 v[160:161], v[202:203], v[160:161]
	v_lshlrev_b32_e32 v202, 16, v123
	v_cvt_pk_bf16_f32 v134, v160, v161
	v_lshlrev_b32_e32 v160, 16, v135
	v_and_b32_e32 v161, 0xffff0000, v135
	v_pk_fma_f32 v[130:131], v[68:69], v[160:161], v[130:131]
	v_and_b32_e32 v203, 0xffff0000, v123
	v_and_b32_e32 v123, 0xffff0000, v143
	v_pk_fma_f32 v[142:143], v[72:73], v[122:123], v[130:131]
	v_and_b32_e32 v127, 0xffff0000, v127
	v_mul_f32_e32 v130, 0xbfb8aa3b, v142
	v_exp_f32_e32 v130, v130
	v_mul_f32_e32 v131, 0xbfb8aa3b, v143
	v_exp_f32_e32 v131, v131
	v_pk_fma_f32 v[126:127], v[46:47], v[126:127], v[58:59]
	v_add_f32_e32 v130, 1.0, v130
	v_rcp_f32_e32 v204, v130
	v_add_f32_e32 v130, 1.0, v131
	v_rcp_f32_e32 v205, v130
	v_pk_fma_f32 v[126:127], v[54:55], v[202:203], v[126:127]
	v_lshlrev_b32_e32 v130, 16, v139
	v_and_b32_e32 v131, 0xffff0000, v139
	v_pk_fma_f32 v[126:127], v[50:51], v[130:131], v[126:127]
	v_pk_mul_f32 v[138:139], v[142:143], v[204:205]
	v_lshlrev_b32_e32 v142, 16, v136
	v_pk_mul_f32 v[126:127], v[126:127], v[138:139]
	v_and_b32_e32 v143, 0xffff0000, v136
	v_cvt_pk_bf16_f32 v135, v126, v127
	v_lshlrev_b32_e32 v126, 16, v132
	v_and_b32_e32 v127, 0xffff0000, v132
	v_pk_fma_f32 v[126:127], v[0:1], v[126:127], v[4:5]
	v_lshlrev_b32_e32 v138, 16, v128
	v_pk_fma_f32 v[204:205], v[24:25], v[142:143], v[126:127]
	v_lshlrev_b32_e32 v126, 16, v144
	v_and_b32_e32 v127, 0xffff0000, v144
	v_pk_fma_f32 v[204:205], v[28:29], v[126:127], v[204:205]
	v_and_b32_e32 v139, 0xffff0000, v128
	v_mul_f32_e32 v124, 0xbfb8aa3b, v204
	v_exp_f32_e32 v124, v124
	v_mul_f32_e32 v128, 0xbfb8aa3b, v205
	v_exp_f32_e32 v128, v128
	v_pk_fma_f32 v[138:139], v[8:9], v[138:139], v[20:21]
	v_add_f32_e32 v124, 1.0, v124
	v_rcp_f32_e32 v210, v124
	v_add_f32_e32 v124, 1.0, v128
	v_rcp_f32_e32 v211, v124
	v_pk_fma_f32 v[208:209], v[16:17], v[206:207], v[138:139]
	v_lshlrev_b32_e32 v138, 16, v140
	v_and_b32_e32 v139, 0xffff0000, v140
	v_pk_fma_f32 v[208:209], v[12:13], v[138:139], v[208:209]
	v_pk_mul_f32 v[204:205], v[204:205], v[210:211]
	v_lshlrev_b32_e32 v132, 16, v133
	v_pk_mul_f32 v[204:205], v[208:209], v[204:205]
	v_and_b32_e32 v133, 0xffff0000, v133
	v_cvt_pk_bf16_f32 v136, v204, v205
	v_pk_fma_f32 v[132:133], v[2:3], v[132:133], v[6:7]
	v_lshlrev_b32_e32 v204, 16, v137
	v_and_b32_e32 v205, 0xffff0000, v137
	v_pk_fma_f32 v[132:133], v[26:27], v[204:205], v[132:133]
	v_lshlrev_b32_e32 v208, 16, v125
	v_and_b32_e32 v209, 0xffff0000, v125
	v_lshlrev_b32_e32 v124, 16, v145
	v_and_b32_e32 v125, 0xffff0000, v145
	v_pk_fma_f32 v[132:133], v[30:31], v[124:125], v[132:133]
	v_lshlrev_b32_e32 v128, 16, v129
	v_mul_f32_e32 v137, 0xbfb8aa3b, v132
	v_exp_f32_e32 v137, v137
	v_mul_f32_e32 v140, 0xbfb8aa3b, v133
	v_exp_f32_e32 v140, v140
	v_and_b32_e32 v129, 0xffff0000, v129
	v_add_f32_e32 v137, 1.0, v137
	v_rcp_f32_e32 v144, v137
	v_add_f32_e32 v137, 1.0, v140
	v_rcp_f32_e32 v145, v137
	v_pk_fma_f32 v[128:129], v[10:11], v[128:129], v[22:23]
	v_lshlrev_b32_e32 v140, 16, v141
	v_pk_fma_f32 v[128:129], v[18:19], v[208:209], v[128:129]
	v_and_b32_e32 v141, 0xffff0000, v141
	v_pk_fma_f32 v[128:129], v[14:15], v[140:141], v[128:129]
	v_pk_mul_f32 v[132:133], v[132:133], v[144:145]
	s_nop 0
	v_pk_mul_f32 v[128:129], v[128:129], v[132:133]
	v_pk_fma_f32 v[132:133], v[44:45], v[162:163], v[56:57]
	v_cvt_pk_bf16_f32 v137, v128, v129
	v_mad_i64_i32 v[128:129], s[0:1], v152, s26, v[146:147]
	global_store_dwordx4 v[128:129], v[134:137], off
	v_pk_fma_f32 v[128:129], v[32:33], v[158:159], v[40:41]
	v_pk_fma_f32 v[132:133], v[52:53], v[150:151], v[132:133]
	v_pk_fma_f32 v[128:129], v[66:67], v[148:149], v[128:129]
	v_lshlrev_b32_e32 v136, 16, v114
	v_and_b32_e32 v137, 0xffff0000, v114
	v_pk_fma_f32 v[128:129], v[70:71], v[136:137], v[128:129]
	v_lshlrev_b32_e32 v162, 16, v106
	v_mul_f32_e32 v114, 0xbfb8aa3b, v128
	v_exp_f32_e32 v114, v114
	v_mul_f32_e32 v134, 0xbfb8aa3b, v129
	v_exp_f32_e32 v135, v134
	v_and_b32_e32 v163, 0xffff0000, v106
	v_add_f32_e32 v114, 1.0, v114
	v_rcp_f32_e32 v134, v114
	v_add_f32_e32 v114, 1.0, v135
	v_rcp_f32_e32 v135, v114
	v_pk_fma_f32 v[132:133], v[48:49], v[162:163], v[132:133]
	v_lshlrev_b32_e32 v158, 16, v108
	v_and_b32_e32 v159, 0xffff0000, v108
	v_pk_mul_f32 v[128:129], v[128:129], v[134:135]
	v_lshlrev_b32_e32 v134, 16, v115
	v_pk_mul_f32 v[128:129], v[132:133], v[128:129]
	v_and_b32_e32 v135, 0xffff0000, v115
	v_cvt_pk_bf16_f32 v114, v128, v129
	v_pk_fma_f32 v[128:129], v[34:35], v[160:161], v[42:43]
	v_pk_fma_f32 v[132:133], v[46:47], v[202:203], v[58:59]
	v_pk_fma_f32 v[128:129], v[68:69], v[122:123], v[128:129]
	v_pk_fma_f32 v[132:133], v[54:55], v[130:131], v[132:133]
	v_pk_fma_f32 v[128:129], v[72:73], v[134:135], v[128:129]
	v_lshlrev_b32_e32 v160, 16, v107
	v_mul_f32_e32 v106, 0xbfb8aa3b, v128
	v_exp_f32_e32 v106, v106
	v_mul_f32_e32 v115, 0xbfb8aa3b, v129
	v_exp_f32_e32 v115, v115
	v_and_b32_e32 v161, 0xffff0000, v107
	v_add_f32_e32 v106, 1.0, v106
	v_rcp_f32_e32 v144, v106
	v_add_f32_e32 v106, 1.0, v115
	v_rcp_f32_e32 v145, v106
	v_pk_fma_f32 v[106:107], v[50:51], v[160:161], v[132:133]
	v_lshlrev_b32_e32 v152, 16, v109
	v_pk_mul_f32 v[128:129], v[128:129], v[144:145]
	s_nop 0
	v_pk_mul_f32 v[106:107], v[106:107], v[128:129]
	v_pk_fma_f32 v[128:129], v[8:9], v[206:207], v[20:21]
	v_cvt_pk_bf16_f32 v115, v106, v107
	v_pk_fma_f32 v[106:107], v[0:1], v[142:143], v[4:5]
	v_pk_fma_f32 v[128:129], v[16:17], v[138:139], v[128:129]
	v_pk_fma_f32 v[132:133], v[24:25], v[126:127], v[106:107]
	v_lshlrev_b32_e32 v106, 16, v116
	v_and_b32_e32 v107, 0xffff0000, v116
	v_pk_fma_f32 v[132:133], v[28:29], v[106:107], v[132:133]
	v_pk_fma_f32 v[128:129], v[12:13], v[158:159], v[128:129]
	v_mul_f32_e32 v116, 0xbfb8aa3b, v132
	v_exp_f32_e32 v116, v116
	v_mul_f32_e32 v142, 0xbfb8aa3b, v133
	v_exp_f32_e32 v143, v142
	v_add_f32_e32 v116, 1.0, v116
	v_rcp_f32_e32 v142, v116
	v_add_f32_e32 v116, 1.0, v143
	v_rcp_f32_e32 v143, v116
	s_nop 0
	v_pk_mul_f32 v[132:133], v[132:133], v[142:143]
	s_nop 0
	v_pk_mul_f32 v[128:129], v[128:129], v[132:133]
	v_lshlrev_b32_e32 v132, 16, v117
	v_cvt_pk_bf16_f32 v116, v128, v129
	v_pk_fma_f32 v[128:129], v[2:3], v[204:205], v[6:7]
	v_and_b32_e32 v133, 0xffff0000, v117
	v_pk_fma_f32 v[128:129], v[26:27], v[124:125], v[128:129]
	v_pk_fma_f32 v[142:143], v[10:11], v[208:209], v[22:23]
	v_pk_fma_f32 v[128:129], v[30:31], v[132:133], v[128:129]
	v_pk_fma_f32 v[142:143], v[18:19], v[140:141], v[142:143]
	v_mul_f32_e32 v108, 0xbfb8aa3b, v128
	v_exp_f32_e32 v108, v108
	v_mul_f32_e32 v117, 0xbfb8aa3b, v129
	v_exp_f32_e32 v117, v117
	v_add_f32_e32 v108, 1.0, v108
	v_rcp_f32_e32 v144, v108
	v_add_f32_e32 v108, 1.0, v117
	v_rcp_f32_e32 v145, v108
	v_pk_fma_f32 v[108:109], v[14:15], v[152:153], v[142:143]
	v_lshlrev_b32_e32 v142, 16, v111
	v_and_b32_e32 v143, 0xffff0000, v111
	v_pk_mul_f32 v[128:129], v[128:129], v[144:145]
	v_lshlrev_b32_e32 v144, 16, v110
	v_pk_mul_f32 v[108:109], v[108:109], v[128:129]
	v_lshlrev_b32_e32 v128, 16, v118
	v_cvt_pk_bf16_f32 v117, v108, v109
	v_mad_i64_i32 v[108:109], s[0:1], v201, s26, v[146:147]
	global_store_dwordx4 v[108:109], v[114:117], off
	v_pk_fma_f32 v[108:109], v[32:33], v[148:149], v[40:41]
	v_and_b32_e32 v129, 0xffff0000, v118
	v_pk_fma_f32 v[108:109], v[66:67], v[136:137], v[108:109]
	v_pk_fma_f32 v[114:115], v[44:45], v[150:151], v[56:57]
	v_pk_fma_f32 v[108:109], v[70:71], v[128:129], v[108:109]
	v_pk_fma_f32 v[114:115], v[52:53], v[162:163], v[114:115]
	v_mul_f32_e32 v116, 0xbfb8aa3b, v108
	v_mul_f32_e32 v117, 0xbfb8aa3b, v109
	v_exp_f32_e32 v116, v116
	v_exp_f32_e32 v117, v117
	v_and_b32_e32 v145, 0xffff0000, v110
	v_pk_fma_f32 v[114:115], v[48:49], v[144:145], v[114:115]
	v_add_f32_e32 v116, 1.0, v116
	v_add_f32_e32 v117, 1.0, v117
	v_rcp_f32_e32 v116, v116
	v_rcp_f32_e32 v117, v117
	v_lshlrev_b32_e32 v118, 16, v119
	v_and_b32_e32 v119, 0xffff0000, v119
	v_pk_mul_f32 v[108:109], v[108:109], v[116:117]
	s_nop 0
	v_pk_mul_f32 v[108:109], v[114:115], v[108:109]
	v_pk_fma_f32 v[114:115], v[34:35], v[122:123], v[42:43]
	v_cvt_pk_bf16_f32 v108, v108, v109
	v_pk_fma_f32 v[114:115], v[68:69], v[134:135], v[114:115]
	v_pk_fma_f32 v[116:117], v[46:47], v[130:131], v[58:59]
	v_pk_fma_f32 v[114:115], v[72:73], v[118:119], v[114:115]
	v_pk_fma_f32 v[116:117], v[54:55], v[160:161], v[116:117]
	v_mul_f32_e32 v109, 0xbfb8aa3b, v114
	v_exp_f32_e32 v109, v109
	v_mul_f32_e32 v110, 0xbfb8aa3b, v115
	v_exp_f32_e32 v110, v110
	s_waitcnt vmcnt(10)
	v_lshlrev_b32_e32 v130, 16, v98
	v_add_f32_e32 v109, 1.0, v109
	v_rcp_f32_e32 v122, v109
	v_add_f32_e32 v109, 1.0, v110
	v_rcp_f32_e32 v123, v109
	v_pk_fma_f32 v[110:111], v[50:51], v[142:143], v[116:117]
	v_lshlrev_b32_e32 v116, 16, v120
	v_and_b32_e32 v117, 0xffff0000, v120
	v_pk_mul_f32 v[114:115], v[114:115], v[122:123]
	v_and_b32_e32 v131, 0xffff0000, v98
	v_pk_mul_f32 v[110:111], v[110:111], v[114:115]
	v_pk_fma_f32 v[114:115], v[8:9], v[138:139], v[20:21]
	v_cvt_pk_bf16_f32 v109, v110, v111
	v_pk_fma_f32 v[110:111], v[0:1], v[126:127], v[4:5]
	v_pk_fma_f32 v[114:115], v[16:17], v[158:159], v[114:115]
	v_pk_fma_f32 v[110:111], v[24:25], v[106:107], v[110:111]
	v_lshlrev_b32_e32 v138, 16, v112
	v_pk_fma_f32 v[110:111], v[28:29], v[116:117], v[110:111]
	v_and_b32_e32 v139, 0xffff0000, v112
	v_mul_f32_e32 v120, 0xbfb8aa3b, v110
	v_exp_f32_e32 v120, v120
	v_mul_f32_e32 v122, 0xbfb8aa3b, v111
	v_exp_f32_e32 v123, v122
	v_pk_fma_f32 v[114:115], v[12:13], v[138:139], v[114:115]
	v_add_f32_e32 v120, 1.0, v120
	v_rcp_f32_e32 v122, v120
	v_add_f32_e32 v120, 1.0, v123
	v_rcp_f32_e32 v123, v120
	v_lshlrev_b32_e32 v126, 16, v99
	v_and_b32_e32 v127, 0xffff0000, v99
	v_pk_mul_f32 v[110:111], v[110:111], v[122:123]
	s_nop 0
	v_pk_mul_f32 v[110:111], v[114:115], v[110:111]
	v_pk_fma_f32 v[114:115], v[2:3], v[124:125], v[6:7]
	v_cvt_pk_bf16_f32 v110, v110, v111
	v_pk_fma_f32 v[124:125], v[26:27], v[132:133], v[114:115]
	v_lshlrev_b32_e32 v114, 16, v121
	v_and_b32_e32 v115, 0xffff0000, v121
	v_pk_fma_f32 v[120:121], v[30:31], v[114:115], v[124:125]
	v_pk_fma_f32 v[122:123], v[10:11], v[140:141], v[22:23]
	v_mul_f32_e32 v111, 0xbfb8aa3b, v120
	v_exp_f32_e32 v111, v111
	v_mul_f32_e32 v112, 0xbfb8aa3b, v121
	v_exp_f32_e32 v112, v112
	v_pk_fma_f32 v[122:123], v[18:19], v[152:153], v[122:123]
	v_add_f32_e32 v111, 1.0, v111
	v_rcp_f32_e32 v124, v111
	v_add_f32_e32 v111, 1.0, v112
	v_rcp_f32_e32 v125, v111
	v_lshlrev_b32_e32 v112, 16, v113
	v_and_b32_e32 v113, 0xffff0000, v113
	v_pk_fma_f32 v[122:123], v[14:15], v[112:113], v[122:123]
	v_pk_mul_f32 v[120:121], v[120:121], v[124:125]
	v_lshlrev_b32_e32 v124, 16, v100
	v_pk_mul_f32 v[120:121], v[122:123], v[120:121]
	v_and_b32_e32 v125, 0xffff0000, v100
	v_cvt_pk_bf16_f32 v111, v120, v121
	v_mad_i64_i32 v[120:121], s[0:1], v199, s26, v[146:147]
	global_store_dwordx4 v[120:121], v[108:111], off
	v_pk_fma_f32 v[120:121], v[44:45], v[162:163], v[56:57]
	s_nop 0
	v_pk_fma_f32 v[108:109], v[32:33], v[136:137], v[40:41]
	v_lshlrev_b32_e32 v110, 16, v102
	v_pk_fma_f32 v[108:109], v[66:67], v[128:129], v[108:109]
	v_and_b32_e32 v111, 0xffff0000, v102
	v_pk_fma_f32 v[108:109], v[70:71], v[110:111], v[108:109]
	v_pk_fma_f32 v[120:121], v[52:53], v[144:145], v[120:121]
	v_mul_f32_e32 v102, 0xbfb8aa3b, v108
	v_exp_f32_e32 v102, v102
	v_mul_f32_e32 v122, 0xbfb8aa3b, v109
	v_exp_f32_e32 v123, v122
	v_pk_fma_f32 v[120:121], v[48:49], v[130:131], v[120:121]
	v_add_f32_e32 v102, 1.0, v102
	v_rcp_f32_e32 v122, v102
	v_add_f32_e32 v102, 1.0, v123
	v_rcp_f32_e32 v123, v102
	s_nop 0
	v_pk_mul_f32 v[108:109], v[108:109], v[122:123]
	s_nop 0
	v_pk_mul_f32 v[108:109], v[120:121], v[108:109]
	v_pk_fma_f32 v[120:121], v[46:47], v[160:161], v[58:59]
	v_cvt_pk_bf16_f32 v98, v108, v109
	v_pk_fma_f32 v[108:109], v[34:35], v[134:135], v[42:43]
	v_pk_fma_f32 v[120:121], v[54:55], v[142:143], v[120:121]
	v_pk_fma_f32 v[122:123], v[68:69], v[118:119], v[108:109]
	v_lshlrev_b32_e32 v108, 16, v103
	v_and_b32_e32 v109, 0xffff0000, v103
	v_pk_fma_f32 v[102:103], v[72:73], v[108:109], v[122:123]
	v_pk_fma_f32 v[120:121], v[50:51], v[126:127], v[120:121]
	v_mul_f32_e32 v122, 0xbfb8aa3b, v102
	v_mul_f32_e32 v123, 0xbfb8aa3b, v103
	v_exp_f32_e32 v122, v122
	v_exp_f32_e32 v123, v123
	v_add_f32_e32 v122, 1.0, v122
	v_add_f32_e32 v123, 1.0, v123
	v_rcp_f32_e32 v122, v122
	v_rcp_f32_e32 v123, v123
	s_nop 0
	v_pk_mul_f32 v[102:103], v[102:103], v[122:123]
	s_nop 0
	v_pk_mul_f32 v[102:103], v[120:121], v[102:103]
	v_pk_fma_f32 v[120:121], v[8:9], v[158:159], v[20:21]
	v_cvt_pk_bf16_f32 v99, v102, v103
	v_pk_fma_f32 v[102:103], v[0:1], v[106:107], v[4:5]
	v_lshlrev_b32_e32 v106, 16, v104
	v_pk_fma_f32 v[102:103], v[24:25], v[116:117], v[102:103]
	v_and_b32_e32 v107, 0xffff0000, v104
	v_pk_fma_f32 v[102:103], v[28:29], v[106:107], v[102:103]
	v_pk_fma_f32 v[120:121], v[16:17], v[138:139], v[120:121]
	v_mul_f32_e32 v104, 0xbfb8aa3b, v102
	v_exp_f32_e32 v104, v104
	v_mul_f32_e32 v122, 0xbfb8aa3b, v103
	v_exp_f32_e32 v123, v122
	v_pk_fma_f32 v[120:121], v[12:13], v[124:125], v[120:121]
	v_add_f32_e32 v104, 1.0, v104
	v_rcp_f32_e32 v122, v104
	v_add_f32_e32 v104, 1.0, v123
	v_rcp_f32_e32 v123, v104
	v_lshlrev_b32_e32 v104, 16, v105
	v_and_b32_e32 v105, 0xffff0000, v105
	v_pk_mul_f32 v[102:103], v[102:103], v[122:123]
	s_nop 0
	v_pk_mul_f32 v[102:103], v[120:121], v[102:103]
	v_pk_fma_f32 v[120:121], v[10:11], v[152:153], v[22:23]
	v_cvt_pk_bf16_f32 v100, v102, v103
	v_pk_fma_f32 v[102:103], v[2:3], v[132:133], v[6:7]
	v_pk_fma_f32 v[120:121], v[18:19], v[112:113], v[120:121]
	v_pk_fma_f32 v[102:103], v[26:27], v[114:115], v[102:103]
	v_pk_fma_f32 v[112:113], v[10:11], v[112:113], v[22:23]
	v_pk_fma_f32 v[102:103], v[30:31], v[104:105], v[102:103]
	s_nop 0
	v_mul_f32_e32 v122, 0xbfb8aa3b, v102
	v_exp_f32_e32 v122, v122
	v_mul_f32_e32 v123, 0xbfb8aa3b, v103
	v_exp_f32_e32 v123, v123
	v_add_f32_e32 v122, 1.0, v122
	v_rcp_f32_e32 v132, v122
	v_add_f32_e32 v122, 1.0, v123
	v_rcp_f32_e32 v133, v122
	v_lshlrev_b32_e32 v122, 16, v101
	v_and_b32_e32 v123, 0xffff0000, v101
	v_pk_fma_f32 v[120:121], v[14:15], v[122:123], v[120:121]
	v_pk_mul_f32 v[102:103], v[102:103], v[132:133]
	s_nop 0
	v_pk_mul_f32 v[102:103], v[120:121], v[102:103]
	s_waitcnt vmcnt(9)
	v_and_b32_e32 v121, 0xffff0000, v90
	v_cvt_pk_bf16_f32 v101, v102, v103
	v_mad_i64_i32 v[102:103], s[0:1], v200, s26, v[146:147]
	global_store_dwordx4 v[102:103], v[98:101], off
	v_lshlrev_b32_e32 v102, 16, v94
	v_and_b32_e32 v103, 0xffff0000, v94
	v_pk_fma_f32 v[98:99], v[32:33], v[128:129], v[40:41]
	v_pk_fma_f32 v[100:101], v[44:45], v[144:145], v[56:57]
	v_pk_fma_f32 v[98:99], v[66:67], v[110:111], v[98:99]
	v_pk_fma_f32 v[100:101], v[52:53], v[130:131], v[100:101]
	v_pk_fma_f32 v[98:99], v[70:71], v[102:103], v[98:99]
	s_nop 0
	v_mul_f32_e32 v94, 0xbfb8aa3b, v98
	v_exp_f32_e32 v94, v94
	v_mul_f32_e32 v120, 0xbfb8aa3b, v99
	v_exp_f32_e32 v120, v120
	v_add_f32_e32 v94, 1.0, v94
	v_rcp_f32_e32 v128, v94
	v_add_f32_e32 v94, 1.0, v120
	v_rcp_f32_e32 v129, v94
	v_lshlrev_b32_e32 v120, 16, v90
	v_pk_fma_f32 v[100:101], v[48:49], v[120:121], v[100:101]
	v_pk_mul_f32 v[98:99], v[98:99], v[128:129]
	s_nop 0
	v_pk_mul_f32 v[98:99], v[100:101], v[98:99]
	v_lshlrev_b32_e32 v100, 16, v95
	v_cvt_pk_bf16_f32 v90, v98, v99
	v_pk_fma_f32 v[98:99], v[34:35], v[118:119], v[42:43]
	v_and_b32_e32 v101, 0xffff0000, v95
	v_pk_fma_f32 v[98:99], v[68:69], v[108:109], v[98:99]
	v_pk_fma_f32 v[118:119], v[46:47], v[142:143], v[58:59]
	v_pk_fma_f32 v[94:95], v[72:73], v[100:101], v[98:99]
	s_nop 0
	v_mul_f32_e32 v98, 0xbfb8aa3b, v94
	v_exp_f32_e32 v128, v98
	v_mul_f32_e32 v98, 0xbfb8aa3b, v95
	v_exp_f32_e32 v129, v98
	v_pk_fma_f32 v[98:99], v[54:55], v[126:127], v[118:119]
	v_add_f32_e32 v118, 1.0, v128
	v_rcp_f32_e32 v128, v118
	v_add_f32_e32 v118, 1.0, v129
	v_rcp_f32_e32 v129, v118
	v_lshlrev_b32_e32 v118, 16, v91
	v_and_b32_e32 v119, 0xffff0000, v91
	v_pk_fma_f32 v[98:99], v[50:51], v[118:119], v[98:99]
	v_pk_mul_f32 v[94:95], v[94:95], v[128:129]
	s_nop 0
	v_pk_mul_f32 v[94:95], v[98:99], v[94:95]
	v_lshlrev_b32_e32 v98, 16, v96
	v_cvt_pk_bf16_f32 v91, v94, v95
	v_pk_fma_f32 v[94:95], v[0:1], v[116:117], v[4:5]
	v_and_b32_e32 v99, 0xffff0000, v96
	v_pk_fma_f32 v[94:95], v[24:25], v[106:107], v[94:95]
	v_pk_fma_f32 v[116:117], v[8:9], v[138:139], v[20:21]
	v_pk_fma_f32 v[94:95], v[28:29], v[98:99], v[94:95]
	s_nop 0
	v_mul_f32_e32 v96, 0xbfb8aa3b, v94
	v_exp_f32_e32 v96, v96
	v_mul_f32_e32 v128, 0xbfb8aa3b, v95
	v_exp_f32_e32 v133, v128
	v_pk_fma_f32 v[128:129], v[16:17], v[124:125], v[116:117]
	v_add_f32_e32 v96, 1.0, v96
	v_rcp_f32_e32 v132, v96
	v_add_f32_e32 v96, 1.0, v133
	v_rcp_f32_e32 v133, v96
	v_lshlrev_b32_e32 v116, 16, v92
	v_and_b32_e32 v117, 0xffff0000, v92
	v_pk_fma_f32 v[128:129], v[12:13], v[116:117], v[128:129]
	v_pk_mul_f32 v[94:95], v[94:95], v[132:133]
	s_nop 0
	v_pk_mul_f32 v[94:95], v[128:129], v[94:95]
	s_nop 0
	v_cvt_pk_bf16_f32 v92, v94, v95
	v_pk_fma_f32 v[94:95], v[2:3], v[114:115], v[6:7]
	s_nop 0
	v_pk_fma_f32 v[114:115], v[26:27], v[104:105], v[94:95]
	v_lshlrev_b32_e32 v94, 16, v97
	v_and_b32_e32 v95, 0xffff0000, v97
	v_pk_fma_f32 v[96:97], v[30:31], v[94:95], v[114:115]
	s_nop 0
	v_mul_f32_e32 v114, 0xbfb8aa3b, v96
	v_exp_f32_e32 v128, v114
	v_mul_f32_e32 v114, 0xbfb8aa3b, v97
	v_exp_f32_e32 v129, v114
	v_pk_fma_f32 v[114:115], v[18:19], v[122:123], v[112:113]
	v_add_f32_e32 v112, 1.0, v128
	v_rcp_f32_e32 v128, v112
	v_add_f32_e32 v112, 1.0, v129
	v_rcp_f32_e32 v129, v112
	v_lshlrev_b32_e32 v112, 16, v93
	v_and_b32_e32 v113, 0xffff0000, v93
	v_pk_fma_f32 v[114:115], v[14:15], v[112:113], v[114:115]
	v_pk_mul_f32 v[96:97], v[96:97], v[128:129]
	s_nop 0
	v_pk_mul_f32 v[96:97], v[114:115], v[96:97]
	s_nop 0
	v_cvt_pk_bf16_f32 v93, v96, v97
	v_mad_i64_i32 v[96:97], s[0:1], v198, s26, v[146:147]
	global_store_dwordx4 v[96:97], v[90:93], off
	v_pk_fma_f32 v[96:97], v[44:45], v[130:131], v[56:57]
	s_nop 0
	v_pk_fma_f32 v[90:91], v[32:33], v[110:111], v[40:41]
	s_waitcnt vmcnt(10)
	v_lshlrev_b32_e32 v92, 16, v86
	v_pk_fma_f32 v[90:91], v[66:67], v[102:103], v[90:91]
	v_and_b32_e32 v93, 0xffff0000, v86
	v_pk_fma_f32 v[90:91], v[70:71], v[92:93], v[90:91]
	v_pk_fma_f32 v[96:97], v[52:53], v[120:121], v[96:97]
	v_mul_f32_e32 v86, 0xbfb8aa3b, v90
	v_exp_f32_e32 v86, v86
	v_mul_f32_e32 v110, 0xbfb8aa3b, v91
	v_exp_f32_e32 v110, v110
	s_waitcnt vmcnt(9)
	v_and_b32_e32 v111, 0xffff0000, v82
	v_add_f32_e32 v86, 1.0, v86
	v_rcp_f32_e32 v114, v86
	v_add_f32_e32 v86, 1.0, v110
	v_rcp_f32_e32 v115, v86
	v_lshlrev_b32_e32 v110, 16, v82
	v_pk_fma_f32 v[96:97], v[48:49], v[110:111], v[96:97]
	v_pk_mul_f32 v[90:91], v[90:91], v[114:115]
	s_nop 0
	v_pk_mul_f32 v[90:91], v[96:97], v[90:91]
	v_pk_fma_f32 v[96:97], v[46:47], v[126:127], v[58:59]
	v_cvt_pk_bf16_f32 v128, v90, v91
	v_pk_fma_f32 v[90:91], v[34:35], v[108:109], v[42:43]
	v_pk_fma_f32 v[96:97], v[54:55], v[118:119], v[96:97]
	v_pk_fma_f32 v[108:109], v[68:69], v[100:101], v[90:91]
	v_lshlrev_b32_e32 v90, 16, v87
	v_and_b32_e32 v91, 0xffff0000, v87
	v_pk_fma_f32 v[86:87], v[72:73], v[90:91], v[108:109]
	v_and_b32_e32 v109, 0xffff0000, v83
	v_mul_f32_e32 v82, 0xbfb8aa3b, v86
	v_exp_f32_e32 v82, v82
	v_mul_f32_e32 v108, 0xbfb8aa3b, v87
	v_exp_f32_e32 v108, v108
	v_add_f32_e32 v82, 1.0, v82
	v_rcp_f32_e32 v114, v82
	v_add_f32_e32 v82, 1.0, v108
	v_rcp_f32_e32 v115, v82
	v_lshlrev_b32_e32 v108, 16, v83
	v_pk_fma_f32 v[82:83], v[50:51], v[108:109], v[96:97]
	v_pk_fma_f32 v[96:97], v[8:9], v[124:125], v[20:21]
	v_pk_mul_f32 v[86:87], v[86:87], v[114:115]
	s_nop 0
	v_pk_mul_f32 v[82:83], v[82:83], v[86:87]
	v_lshlrev_b32_e32 v86, 16, v88
	v_cvt_pk_bf16_f32 v129, v82, v83
	v_pk_fma_f32 v[82:83], v[0:1], v[106:107], v[4:5]
	v_and_b32_e32 v87, 0xffff0000, v88
	v_pk_fma_f32 v[82:83], v[24:25], v[98:99], v[82:83]
	s_nop 0
	v_pk_fma_f32 v[82:83], v[28:29], v[86:87], v[82:83]
	s_nop 0
	v_mul_f32_e32 v88, 0xbfb8aa3b, v82
	v_exp_f32_e32 v88, v88
	v_mul_f32_e32 v106, 0xbfb8aa3b, v83
	v_exp_f32_e32 v115, v106
	v_pk_fma_f32 v[106:107], v[16:17], v[116:117], v[96:97]
	v_add_f32_e32 v88, 1.0, v88
	v_rcp_f32_e32 v114, v88
	v_add_f32_e32 v88, 1.0, v115
	v_rcp_f32_e32 v115, v88
	v_lshlrev_b32_e32 v96, 16, v84
	v_and_b32_e32 v97, 0xffff0000, v84
	v_pk_fma_f32 v[106:107], v[12:13], v[96:97], v[106:107]
	v_pk_mul_f32 v[82:83], v[82:83], v[114:115]
	s_waitcnt vmcnt(7)
	v_lshlrev_b32_e32 v114, 16, v74
	v_pk_mul_f32 v[82:83], v[106:107], v[82:83]
	v_and_b32_e32 v115, 0xffff0000, v74
	v_cvt_pk_bf16_f32 v130, v82, v83
	v_pk_fma_f32 v[82:83], v[2:3], v[104:105], v[6:7]
	v_pk_fma_f32 v[104:105], v[10:11], v[122:123], v[22:23]
	v_pk_fma_f32 v[106:107], v[26:27], v[94:95], v[82:83]
	v_lshlrev_b32_e32 v82, 16, v89
	v_and_b32_e32 v83, 0xffff0000, v89
	v_pk_fma_f32 v[88:89], v[30:31], v[82:83], v[106:107]
	v_pk_fma_f32 v[104:105], v[18:19], v[112:113], v[104:105]
	v_mul_f32_e32 v84, 0xbfb8aa3b, v88
	v_exp_f32_e32 v84, v84
	v_mul_f32_e32 v106, 0xbfb8aa3b, v89
	v_exp_f32_e32 v107, v106
	v_add_f32_e32 v84, 1.0, v84
	v_rcp_f32_e32 v106, v84
	v_add_f32_e32 v84, 1.0, v107
	v_rcp_f32_e32 v107, v84
	v_lshlrev_b32_e32 v84, 16, v85
	v_and_b32_e32 v85, 0xffff0000, v85
	v_pk_fma_f32 v[104:105], v[14:15], v[84:85], v[104:105]
	v_pk_mul_f32 v[88:89], v[88:89], v[106:107]
	s_nop 0
	v_pk_mul_f32 v[88:89], v[104:105], v[88:89]
	v_lshlrev_b32_e32 v104, 16, v78
	v_cvt_pk_bf16_f32 v131, v88, v89
	v_mad_i64_i32 v[88:89], s[0:1], v197, s26, v[146:147]
	global_store_dwordx4 v[88:89], v[128:131], off
	v_pk_fma_f32 v[88:89], v[32:33], v[102:103], v[40:41]
	v_and_b32_e32 v105, 0xffff0000, v78
	v_pk_fma_f32 v[88:89], v[66:67], v[92:93], v[88:89]
	v_pk_fma_f32 v[102:103], v[44:45], v[120:121], v[56:57]
	v_pk_fma_f32 v[88:89], v[70:71], v[104:105], v[88:89]
	v_pk_fma_f32 v[102:103], v[52:53], v[110:111], v[102:103]
	v_mul_f32_e32 v78, 0xbfb8aa3b, v88
	v_exp_f32_e32 v78, v78
	v_mul_f32_e32 v106, 0xbfb8aa3b, v89
	v_exp_f32_e32 v107, v106
	v_pk_fma_f32 v[102:103], v[48:49], v[114:115], v[102:103]
	v_add_f32_e32 v78, 1.0, v78
	v_rcp_f32_e32 v106, v78
	v_add_f32_e32 v78, 1.0, v107
	v_rcp_f32_e32 v107, v78
	v_lshlrev_b32_e32 v78, 16, v79
	v_and_b32_e32 v79, 0xffff0000, v79
	v_pk_fma_f32 v[32:33], v[32:33], v[92:93], v[40:41]
	v_pk_mul_f32 v[88:89], v[88:89], v[106:107]
	v_pk_fma_f32 v[40:41], v[44:45], v[110:111], v[56:57]
	v_pk_mul_f32 v[88:89], v[102:103], v[88:89]
	v_pk_fma_f32 v[32:33], v[66:67], v[104:105], v[32:33]
	v_cvt_pk_bf16_f32 v74, v88, v89
	v_pk_fma_f32 v[88:89], v[34:35], v[100:101], v[42:43]
	s_waitcnt vmcnt(6)
	v_lshlrev_b32_e32 v44, 16, v60
	v_pk_fma_f32 v[88:89], v[68:69], v[90:91], v[88:89]
	v_and_b32_e32 v45, 0xffff0000, v60
	v_pk_fma_f32 v[88:89], v[72:73], v[78:79], v[88:89]
	v_pk_fma_f32 v[32:33], v[70:71], v[44:45], v[32:33]
	v_mul_f32_e32 v102, 0xbfb8aa3b, v88
	v_mul_f32_e32 v103, 0xbfb8aa3b, v89
	v_exp_f32_e32 v102, v102
	v_exp_f32_e32 v103, v103
	v_mul_f32_e32 v44, 0xbfb8aa3b, v32
	v_mul_f32_e32 v45, 0xbfb8aa3b, v33
	v_exp_f32_e32 v44, v44
	v_exp_f32_e32 v45, v45
	v_add_f32_e32 v102, 1.0, v102
	v_add_f32_e32 v103, 1.0, v103
	v_rcp_f32_e32 v102, v102
	v_rcp_f32_e32 v103, v103
	v_pk_fma_f32 v[100:101], v[46:47], v[118:119], v[58:59]
	v_add_f32_e32 v44, 1.0, v44
	v_add_f32_e32 v45, 1.0, v45
	v_pk_fma_f32 v[100:101], v[54:55], v[108:109], v[100:101]
	v_lshlrev_b32_e32 v106, 16, v75
	v_and_b32_e32 v107, 0xffff0000, v75
	v_rcp_f32_e32 v44, v44
	v_rcp_f32_e32 v45, v45
	v_pk_fma_f32 v[100:101], v[50:51], v[106:107], v[100:101]
	v_pk_mul_f32 v[88:89], v[88:89], v[102:103]
	v_pk_fma_f32 v[40:41], v[52:53], v[114:115], v[40:41]
	v_pk_mul_f32 v[88:89], v[100:101], v[88:89]
	v_lshlrev_b32_e32 v52, 16, v36
	v_cvt_pk_bf16_f32 v75, v88, v89
	v_pk_fma_f32 v[88:89], v[0:1], v[98:99], v[4:5]
	v_and_b32_e32 v53, 0xffff0000, v36
	v_pk_fma_f32 v[34:35], v[34:35], v[90:91], v[42:43]
	v_pk_fma_f32 v[88:89], v[24:25], v[86:87], v[88:89]
	v_lshlrev_b32_e32 v100, 16, v80
	v_and_b32_e32 v101, 0xffff0000, v80
	v_pk_fma_f32 v[40:41], v[48:49], v[52:53], v[40:41]
	v_pk_mul_f32 v[32:33], v[32:33], v[44:45]
	v_pk_fma_f32 v[34:35], v[68:69], v[78:79], v[34:35]
	v_lshlrev_b32_e32 v42, 16, v61
	v_and_b32_e32 v43, 0xffff0000, v61
	v_pk_fma_f32 v[0:1], v[0:1], v[86:87], v[4:5]
	v_pk_fma_f32 v[98:99], v[8:9], v[116:117], v[20:21]
	v_pk_fma_f32 v[88:89], v[28:29], v[100:101], v[88:89]
	v_pk_mul_f32 v[32:33], v[40:41], v[32:33]
	v_pk_fma_f32 v[34:35], v[72:73], v[42:43], v[34:35]
	v_pk_fma_f32 v[4:5], v[8:9], v[96:97], v[20:21]
	v_pk_fma_f32 v[0:1], v[24:25], v[100:101], v[0:1]
	v_lshlrev_b32_e32 v8, 16, v62
	v_and_b32_e32 v9, 0xffff0000, v62
	v_mul_f32_e32 v80, 0xbfb8aa3b, v88
	v_cvt_pk_bf16_f32 v32, v32, v33
	v_mul_f32_e32 v33, 0xbfb8aa3b, v34
	v_pk_fma_f32 v[0:1], v[28:29], v[8:9], v[0:1]
	v_exp_f32_e32 v80, v80
	v_mul_f32_e32 v102, 0xbfb8aa3b, v89
	v_exp_f32_e32 v33, v33
	v_mul_f32_e32 v36, 0xbfb8aa3b, v35
	v_mul_f32_e32 v8, 0xbfb8aa3b, v0
	v_mul_f32_e32 v9, 0xbfb8aa3b, v1
	v_exp_f32_e32 v103, v102
	v_exp_f32_e32 v36, v36
	v_exp_f32_e32 v8, v8
	v_exp_f32_e32 v9, v9
	v_add_f32_e32 v80, 1.0, v80
	v_add_f32_e32 v33, 1.0, v33
	v_rcp_f32_e32 v102, v80
	v_add_f32_e32 v80, 1.0, v103
	v_rcp_f32_e32 v42, v33
	v_add_f32_e32 v33, 1.0, v36
	v_add_f32_e32 v8, 1.0, v8
	v_add_f32_e32 v9, 1.0, v9
	v_rcp_f32_e32 v103, v80
	v_rcp_f32_e32 v43, v33
	v_rcp_f32_e32 v8, v8
	v_rcp_f32_e32 v9, v9
	v_lshlrev_b32_e32 v116, 16, v76
	v_and_b32_e32 v117, 0xffff0000, v76
	v_pk_fma_f32 v[40:41], v[46:47], v[108:109], v[58:59]
	v_pk_fma_f32 v[98:99], v[16:17], v[96:97], v[98:99]
	v_pk_fma_f32 v[40:41], v[54:55], v[106:107], v[40:41]
	v_lshlrev_b32_e32 v36, 16, v37
	v_and_b32_e32 v37, 0xffff0000, v37
	v_pk_fma_f32 v[4:5], v[16:17], v[116:117], v[4:5]
	v_lshlrev_b32_e32 v16, 16, v38
	v_and_b32_e32 v17, 0xffff0000, v38
	v_pk_fma_f32 v[98:99], v[12:13], v[116:117], v[98:99]
	v_pk_mul_f32 v[88:89], v[88:89], v[102:103]
	v_pk_fma_f32 v[36:37], v[50:51], v[36:37], v[40:41]
	v_pk_mul_f32 v[34:35], v[34:35], v[42:43]
	v_pk_fma_f32 v[4:5], v[12:13], v[16:17], v[4:5]
	v_pk_mul_f32 v[0:1], v[0:1], v[8:9]
	v_pk_mul_f32 v[88:89], v[98:99], v[88:89]
	v_pk_mul_f32 v[34:35], v[36:37], v[34:35]
	v_pk_mul_f32 v[0:1], v[4:5], v[0:1]
	v_cvt_pk_bf16_f32 v76, v88, v89
	v_pk_fma_f32 v[88:89], v[2:3], v[94:95], v[6:7]
	v_lshlrev_b32_e32 v80, 16, v81
	v_and_b32_e32 v81, 0xffff0000, v81
	v_cvt_pk_bf16_f32 v33, v34, v35
	v_cvt_pk_bf16_f32 v34, v0, v1
	v_pk_fma_f32 v[0:1], v[2:3], v[82:83], v[6:7]
	v_pk_fma_f32 v[88:89], v[26:27], v[82:83], v[88:89]
	v_pk_fma_f32 v[0:1], v[26:27], v[80:81], v[0:1]
	v_lshlrev_b32_e32 v4, 16, v63
	v_and_b32_e32 v5, 0xffff0000, v63
	v_pk_fma_f32 v[88:89], v[30:31], v[80:81], v[88:89]
	v_pk_fma_f32 v[0:1], v[30:31], v[4:5], v[0:1]
	v_mul_f32_e32 v98, 0xbfb8aa3b, v88
	v_mul_f32_e32 v99, 0xbfb8aa3b, v89
	v_mul_f32_e32 v4, 0xbfb8aa3b, v0
	v_mul_f32_e32 v5, 0xbfb8aa3b, v1
	v_exp_f32_e32 v98, v98
	v_exp_f32_e32 v99, v99
	v_exp_f32_e32 v4, v4
	v_exp_f32_e32 v5, v5
	v_add_f32_e32 v98, 1.0, v98
	v_add_f32_e32 v99, 1.0, v99
	v_add_f32_e32 v4, 1.0, v4
	v_add_f32_e32 v5, 1.0, v5
	v_rcp_f32_e32 v98, v98
	v_rcp_f32_e32 v99, v99
	v_rcp_f32_e32 v4, v4
	v_rcp_f32_e32 v5, v5
	v_pk_fma_f32 v[94:95], v[10:11], v[112:113], v[22:23]
	v_lshlrev_b32_e32 v102, 16, v77
	v_and_b32_e32 v103, 0xffff0000, v77
	v_pk_fma_f32 v[2:3], v[10:11], v[84:85], v[22:23]
	v_pk_fma_f32 v[94:95], v[18:19], v[84:85], v[94:95]
	v_pk_fma_f32 v[2:3], v[18:19], v[102:103], v[2:3]
	v_lshlrev_b32_e32 v6, 16, v39
	v_and_b32_e32 v7, 0xffff0000, v39
	v_pk_fma_f32 v[94:95], v[14:15], v[102:103], v[94:95]
	v_pk_mul_f32 v[88:89], v[88:89], v[98:99]
	v_pk_fma_f32 v[2:3], v[14:15], v[6:7], v[2:3]
	v_pk_mul_f32 v[0:1], v[0:1], v[4:5]
	v_pk_mul_f32 v[88:89], v[94:95], v[88:89]
	v_pk_mul_f32 v[0:1], v[2:3], v[0:1]
	v_cvt_pk_bf16_f32 v77, v88, v89
	v_mad_i64_i32 v[88:89], s[0:1], v165, s26, v[146:147]
	v_cvt_pk_bf16_f32 v35, v0, v1
	v_mad_i64_i32 v[0:1], s[0:1], v164, s26, v[146:147]
	v_readlane_b32 s0, v242, 17
	s_nop 1
	s_cmp_eq_u32 s96, 1
	s_cselect_b32 s0, 0x10000, s0
	global_store_dwordx4 v[88:89], v[74:77], off
	global_store_dwordx4 v[0:1], v[32:35], off
	v_add_u32_e32 v64, s0, v64
	s_mov_b32 s0, 0xaffff
	s_cmp_eq_u32 s96, 1
	s_cselect_b32 s0, 0x33fff, s0
	v_cmp_lt_i32_e32 vcc, s0, v64
	s_or_b64 s[28:29], vcc, s[28:29]
	s_andn2_b64 exec, exec, s[28:29]
	s_cbranch_execz .LBB0_1727

.LBB0_1727:
	s_or_b64 exec, exec, s[24:25]
	s_cmp_eq_u32 s96, 1
	s_cbranch_scc0 .Lcv_p2
	s_mov_b32 s96, 2
	s_waitcnt vmcnt(0)
	s_branch .LBB0_1667
